# P4/P9 rmsnorm+modulate: shift/scale vectors of column chunks 1..3 fetched at the top of the row iteration (one wait) instead of a load group + wait ladder per chunk behind the previous store, on v195
# speedup vs baseline: 1.0014x; 1.0013x over previous
.LBB0_439:
	global_load_dwordx4 v[36:39], v[34:35], off nt
	global_load_dwordx4 v[40:43], v[34:35], off offset:1024 nt
	global_load_dwordx4 v[56:59], v[34:35], off offset:2048 nt
	global_load_dwordx4 v[60:63], v[34:35], off offset:3072 nt
	s_ashr_i32 s6, s12, 12
	s_mul_hi_i32 s7, s6, 0x12000
	s_mul_i32 s6, s6, 0x12000
	s_add_u32 s8, s50, s6
	s_addc_u32 s9, s51, s7
	s_add_u32 s6, s8, 0x6000
	s_addc_u32 s7, s9, 0
	s_add_u32 s8, s8, 0x8000
	s_addc_u32 s9, s9, 0
	global_load_dwordx4 v[64:67], v51, s[6:7] offset:16
	global_load_dwordx4 v[68:71], v51, s[6:7]
	global_load_dwordx4 v[72:75], v51, s[8:9] offset:16
	global_load_dwordx4 v[76:79], v51, s[8:9]
	global_load_dwordx4 v[130:133], v52, s[8:9]
	global_load_dwordx4 v[134:137], v52, s[8:9] offset:16
	global_load_dwordx4 v[138:141], v52, s[6:7]
	global_load_dwordx4 v[142:145], v52, s[6:7] offset:16
	global_load_dwordx4 v[146:149], v53, s[8:9]
	global_load_dwordx4 v[150:153], v53, s[8:9] offset:16
	global_load_dwordx4 v[154:157], v53, s[6:7]
	global_load_dwordx4 v[158:161], v53, s[6:7] offset:16
	global_load_dwordx4 v[162:165], v54, s[8:9]
	global_load_dwordx4 v[166:169], v54, s[8:9] offset:16
	global_load_dwordx4 v[170:173], v54, s[6:7]
	global_load_dwordx4 v[174:177], v54, s[6:7] offset:16
	v_add_co_u32_e32 v80, vcc, s10, v34
	s_add_i32 s12, s12, s101
	s_nop 0
	v_addc_co_u32_e32 v81, vcc, -1, v35, vcc
	s_cmp_lt_i32 s12, s100
	s_waitcnt vmcnt(0)
	v_cvt_f32_f16_sdwa v83, v36 dst_sel:DWORD dst_unused:UNUSED_PAD src0_sel:WORD_1
	v_cvt_f32_f16_sdwa v85, v37 dst_sel:DWORD dst_unused:UNUSED_PAD src0_sel:WORD_1
	v_cvt_f32_f16_sdwa v87, v38 dst_sel:DWORD dst_unused:UNUSED_PAD src0_sel:WORD_1
	v_cvt_f32_f16_sdwa v89, v39 dst_sel:DWORD dst_unused:UNUSED_PAD src0_sel:WORD_1
	v_cvt_f32_f16_e32 v82, v36
	v_cvt_f32_f16_e32 v84, v37
	v_cvt_f32_f16_e32 v86, v38
	v_cvt_f32_f16_e32 v88, v39
	v_cvt_f32_f16_sdwa v91, v40 dst_sel:DWORD dst_unused:UNUSED_PAD src0_sel:WORD_1
	v_cvt_f32_f16_sdwa v93, v41 dst_sel:DWORD dst_unused:UNUSED_PAD src0_sel:WORD_1
	v_cvt_f32_f16_e32 v90, v40
	v_cvt_f32_f16_e32 v92, v41
	v_cvt_f32_f16_e32 v94, v42
	v_cvt_f32_f16_e32 v96, v43
	v_cvt_f32_f16_sdwa v95, v42 dst_sel:DWORD dst_unused:UNUSED_PAD src0_sel:WORD_1
	v_cvt_f32_f16_sdwa v97, v43 dst_sel:DWORD dst_unused:UNUSED_PAD src0_sel:WORD_1
	v_cvt_f32_f16_sdwa v99, v56 dst_sel:DWORD dst_unused:UNUSED_PAD src0_sel:WORD_1
	v_cvt_f32_f16_e32 v98, v56
	v_cvt_f32_f16_sdwa v101, v57 dst_sel:DWORD dst_unused:UNUSED_PAD src0_sel:WORD_1
	v_cvt_f32_f16_e32 v100, v57
	v_cvt_f32_f16_sdwa v103, v58 dst_sel:DWORD dst_unused:UNUSED_PAD src0_sel:WORD_1
	v_cvt_f32_f16_e32 v102, v58
	v_cvt_f32_f16_sdwa v105, v59 dst_sel:DWORD dst_unused:UNUSED_PAD src0_sel:WORD_1
	v_cvt_f32_f16_e32 v104, v59
	v_cvt_f32_f16_sdwa v39, v62 dst_sel:DWORD dst_unused:UNUSED_PAD src0_sel:WORD_1
	v_cvt_f32_f16_e32 v38, v62
	v_cvt_f32_f16_sdwa v43, v63 dst_sel:DWORD dst_unused:UNUSED_PAD src0_sel:WORD_1
	v_cvt_f32_f16_e32 v42, v63
	v_mov_b32_e32 v58, v83
	v_mov_b32_e32 v59, v87
	v_mov_b32_e32 v62, v85
	v_mov_b32_e32 v63, v89
	v_cvt_f32_f16_sdwa v37, v60 dst_sel:DWORD dst_unused:UNUSED_PAD src0_sel:WORD_1
	v_cvt_f32_f16_e32 v36, v60
	v_cvt_f32_f16_sdwa v41, v61 dst_sel:DWORD dst_unused:UNUSED_PAD src0_sel:WORD_1
	v_cvt_f32_f16_e32 v40, v61
	v_mov_b32_e32 v56, v82
	v_mov_b32_e32 v57, v86
	v_mov_b32_e32 v60, v84
	v_mov_b32_e32 v61, v88
	v_mov_b32_e32 v108, v91
	v_mov_b32_e32 v109, v93
	v_pk_mul_f32 v[58:59], v[58:59], v[58:59]
	v_pk_mul_f32 v[62:63], v[62:63], v[62:63]
	v_mov_b32_e32 v106, v90
	v_mov_b32_e32 v107, v92
	v_pk_mul_f32 v[108:109], v[108:109], v[108:109]
	v_pk_fma_f32 v[56:57], v[56:57], v[56:57], v[58:59]
	v_pk_fma_f32 v[58:59], v[60:61], v[60:61], v[62:63]
	v_mul_f32_e32 v110, v94, v94
	v_mul_f32_e32 v112, v96, v96
	v_pk_fma_f32 v[60:61], v[106:107], v[106:107], v[108:109]
	v_pk_add_f32 v[56:57], v[56:57], v[58:59]
	v_pk_mul_f32 v[114:115], v[98:99], v[98:99]
	v_pk_mul_f32 v[116:117], v[100:101], v[100:101]
	v_pk_fma_f32 v[110:111], v[94:95], v[94:95], v[110:111] op_sel_hi:[1,1,0]
	v_pk_fma_f32 v[112:113], v[96:97], v[96:97], v[112:113] op_sel_hi:[1,1,0]
	v_pk_add_f32 v[58:59], v[60:61], v[60:61] op_sel_hi:[0,1]
	v_pk_add_f32 v[56:57], v[56:57], v[56:57] op_sel_hi:[0,1]
	v_mov_b32_e32 v120, v103
	v_mov_b32_e32 v121, v105
	v_mov_b32_e32 v110, v114
	v_mov_b32_e32 v112, v115
	v_mov_b32_e32 v58, v117
	v_mov_b32_e32 v56, v116
	v_mov_b32_e32 v118, v102
	v_mov_b32_e32 v119, v104
	v_pk_mul_f32 v[120:121], v[120:121], v[120:121]
	v_pk_add_f32 v[60:61], v[110:111], v[112:113]
	v_pk_add_f32 v[56:57], v[56:57], v[58:59]
	v_mul_f32_e32 v122, v36, v36
	v_mul_f32_e32 v124, v40, v40
	v_pk_fma_f32 v[62:63], v[118:119], v[118:119], v[120:121]
	v_pk_add_f32 v[56:57], v[60:61], v[56:57]
	v_pk_mul_f32 v[126:127], v[38:39], v[38:39]
	v_pk_mul_f32 v[128:129], v[42:43], v[42:43]
	v_pk_fma_f32 v[122:123], v[36:37], v[36:37], v[122:123] op_sel_hi:[1,1,0]
	v_pk_fma_f32 v[124:125], v[40:41], v[40:41], v[124:125] op_sel_hi:[1,1,0]
	v_pk_add_f32 v[62:63], v[62:63], v[62:63] op_sel_hi:[0,1]
	v_pk_add_f32 v[56:57], v[56:57], v[56:57] op_sel_hi:[0,1]
	v_mov_b32_e32 v122, v126
	v_mov_b32_e32 v124, v127
	v_mov_b32_e32 v62, v128
	v_mov_b32_e32 v56, v129
	v_pk_add_f32 v[106:107], v[122:123], v[124:125]
	v_pk_add_f32 v[56:57], v[62:63], v[56:57]
	v_pk_add_f32 v[78:79], v[78:79], 1.0 op_sel_hi:[1,0]
	v_pk_add_f32 v[56:57], v[106:107], v[56:57]
	v_pk_add_f32 v[76:77], v[76:77], 1.0 op_sel_hi:[1,0]
	v_add_f32_e32 v55, v56, v57
	ds_bpermute_b32 v56, v44, v55
	v_pk_add_f32 v[74:75], v[74:75], 1.0 op_sel_hi:[1,0]
	v_pk_add_f32 v[72:73], v[72:73], 1.0 op_sel_hi:[1,0]
	s_waitcnt lgkmcnt(0)
	v_add_f32_e32 v55, v55, v56
	ds_bpermute_b32 v56, v45, v55
	s_waitcnt lgkmcnt(0)
	v_add_f32_e32 v55, v55, v56
	ds_bpermute_b32 v56, v46, v55
	s_waitcnt lgkmcnt(0)
	v_add_f32_e32 v55, v55, v56
	ds_bpermute_b32 v56, v47, v55
	s_waitcnt lgkmcnt(0)
	v_add_f32_e32 v55, v55, v56
	ds_bpermute_b32 v56, v48, v55
	s_waitcnt lgkmcnt(0)
	v_add_f32_e32 v55, v55, v56
	ds_bpermute_b32 v56, v49, v55
	s_waitcnt lgkmcnt(0)
	v_add_f32_e32 v55, v55, v56
	v_fmamk_f32 v55, v55, 0x3a000000, v50
	v_rsq_f32_e32 v106, v55
	s_nop 0
	v_pk_mul_f32 v[56:57], v[84:85], v[106:107] op_sel_hi:[1,0]
	v_pk_mul_f32 v[58:59], v[82:83], v[106:107] op_sel_hi:[1,0]
	v_pk_mul_f32 v[60:61], v[88:89], v[106:107] op_sel_hi:[1,0]
	v_pk_mul_f32 v[62:63], v[86:87], v[106:107] op_sel_hi:[1,0]
	v_pk_mul_f32 v[58:59], v[6:7], v[58:59]
	v_pk_mul_f32 v[56:57], v[8:9], v[56:57]
	v_pk_mul_f32 v[62:63], v[2:3], v[62:63]
	v_pk_mul_f32 v[60:61], v[4:5], v[60:61]
	v_pk_fma_f32 v[70:71], v[78:79], v[56:57], v[70:71]
	v_pk_fma_f32 v[56:57], v[76:77], v[58:59], v[68:69]
	v_pk_fma_f32 v[60:61], v[74:75], v[60:61], v[66:67]
	v_pk_fma_f32 v[58:59], v[72:73], v[62:63], v[64:65]
	v_cvt_pk_bf16_f32 v56, v56, v57
	v_cvt_pk_bf16_f32 v57, v70, v71
	v_cvt_pk_bf16_f32 v58, v58, v59
	v_cvt_pk_bf16_f32 v59, v60, v61
	global_store_dwordx4 v[80:81], v[56:59], off sc1
	v_pk_mul_f32 v[74:75], v[92:93], v[106:107] op_sel_hi:[1,0]
	v_pk_mul_f32 v[76:77], v[90:91], v[106:107] op_sel_hi:[1,0]
	v_pk_mul_f32 v[78:79], v[96:97], v[106:107] op_sel_hi:[1,0]
	v_pk_mul_f32 v[80:81], v[94:95], v[106:107] op_sel_hi:[1,0]
	v_pk_mul_f32 v[76:77], v[14:15], v[76:77]
	v_pk_mul_f32 v[74:75], v[16:17], v[74:75]
	v_pk_mul_f32 v[80:81], v[10:11], v[80:81]
	v_pk_mul_f32 v[78:79], v[12:13], v[78:79]
	v_add_co_u32_e32 v72, vcc, s11, v34
	v_pk_mul_f32 v[40:41], v[40:41], v[106:107] op_sel_hi:[1,0]
	s_nop 0
	v_addc_co_u32_e32 v73, vcc, -1, v35, vcc
	v_pk_mul_f32 v[36:37], v[36:37], v[106:107] op_sel_hi:[1,0]
	v_pk_mul_f32 v[42:43], v[42:43], v[106:107] op_sel_hi:[1,0]
	v_pk_mul_f32 v[38:39], v[38:39], v[106:107] op_sel_hi:[1,0]
	v_pk_mul_f32 v[36:37], v[30:31], v[36:37]
	v_pk_mul_f32 v[40:41], v[32:33], v[40:41]
	v_pk_mul_f32 v[38:39], v[26:27], v[38:39]
	v_pk_mul_f32 v[42:43], v[28:29], v[42:43]
	v_lshl_add_u64 v[34:35], v[34:35], 0, s[0:1]
	v_pk_add_f32 v[58:59], v[132:133], 1.0 op_sel_hi:[1,0]
	v_pk_add_f32 v[56:57], v[130:131], 1.0 op_sel_hi:[1,0]
	v_pk_add_f32 v[62:63], v[136:137], 1.0 op_sel_hi:[1,0]
	v_pk_add_f32 v[60:61], v[134:135], 1.0 op_sel_hi:[1,0]
	v_pk_fma_f32 v[58:59], v[58:59], v[74:75], v[140:141]
	v_pk_fma_f32 v[56:57], v[56:57], v[76:77], v[138:139]
	v_pk_fma_f32 v[62:63], v[62:63], v[78:79], v[144:145]
	v_pk_fma_f32 v[60:61], v[60:61], v[80:81], v[142:143]
	v_cvt_pk_bf16_f32 v56, v56, v57
	v_cvt_pk_bf16_f32 v57, v58, v59
	v_cvt_pk_bf16_f32 v58, v60, v61
	v_cvt_pk_bf16_f32 v59, v62, v63
	global_store_dwordx4 v[72:73], v[56:59], off offset:-3072 sc1
	v_pk_mul_f32 v[74:75], v[100:101], v[106:107] op_sel_hi:[1,0]
	v_pk_mul_f32 v[76:77], v[98:99], v[106:107] op_sel_hi:[1,0]
	v_pk_mul_f32 v[78:79], v[104:105], v[106:107] op_sel_hi:[1,0]
	v_pk_mul_f32 v[80:81], v[102:103], v[106:107] op_sel_hi:[1,0]
	v_pk_mul_f32 v[76:77], v[22:23], v[76:77]
	v_pk_mul_f32 v[74:75], v[24:25], v[74:75]
	v_pk_mul_f32 v[80:81], v[18:19], v[80:81]
	v_pk_mul_f32 v[78:79], v[20:21], v[78:79]
	v_pk_add_f32 v[58:59], v[148:149], 1.0 op_sel_hi:[1,0]
	v_pk_add_f32 v[56:57], v[146:147], 1.0 op_sel_hi:[1,0]
	v_pk_add_f32 v[62:63], v[152:153], 1.0 op_sel_hi:[1,0]
	v_pk_add_f32 v[60:61], v[150:151], 1.0 op_sel_hi:[1,0]
	v_pk_fma_f32 v[58:59], v[58:59], v[74:75], v[156:157]
	v_pk_fma_f32 v[56:57], v[56:57], v[76:77], v[154:155]
	v_pk_fma_f32 v[62:63], v[62:63], v[78:79], v[160:161]
	v_pk_fma_f32 v[60:61], v[60:61], v[80:81], v[158:159]
	v_cvt_pk_bf16_f32 v56, v56, v57
	v_cvt_pk_bf16_f32 v57, v58, v59
	v_cvt_pk_bf16_f32 v58, v60, v61
	v_cvt_pk_bf16_f32 v59, v62, v63
	global_store_dwordx4 v[72:73], v[56:59], off offset:-2048 sc1
	v_pk_add_f32 v[62:63], v[168:169], 1.0 op_sel_hi:[1,0]
	v_pk_add_f32 v[60:61], v[166:167], 1.0 op_sel_hi:[1,0]
	s_nop 0
	v_pk_add_f32 v[58:59], v[164:165], 1.0 op_sel_hi:[1,0]
	v_pk_add_f32 v[56:57], v[162:163], 1.0 op_sel_hi:[1,0]
	v_pk_fma_f32 v[40:41], v[58:59], v[40:41], v[172:173]
	v_pk_fma_f32 v[36:37], v[56:57], v[36:37], v[170:171]
	v_pk_fma_f32 v[42:43], v[42:43], v[62:63], v[176:177]
	v_pk_fma_f32 v[38:39], v[38:39], v[60:61], v[174:175]
	v_cvt_pk_bf16_f32 v36, v36, v37
	v_cvt_pk_bf16_f32 v37, v40, v41
	v_cvt_pk_bf16_f32 v38, v38, v39
	v_cvt_pk_bf16_f32 v39, v42, v43
	global_store_dwordx4 v[72:73], v[36:39], off offset:-1024 sc1
	s_cbranch_scc1 .LBB0_439

.LBB0_921:
	global_load_dwordx4 v[36:39], v[34:35], off nt
	global_load_dwordx4 v[40:43], v[34:35], off offset:1024 nt
	global_load_dwordx4 v[56:59], v[34:35], off offset:2048 nt
	global_load_dwordx4 v[60:63], v[34:35], off offset:3072 nt
	s_ashr_i32 s6, s98, 12
	s_mul_hi_i32 s7, s6, 0x12000
	s_mul_i32 s6, s6, 0x12000
	s_add_u32 s8, s50, s6
	s_addc_u32 s9, s51, s7
	s_add_u32 s6, s8, 0xc000
	s_addc_u32 s7, s9, 0
	s_add_u32 s8, s8, 0xe000
	s_addc_u32 s9, s9, 0
	global_load_dwordx4 v[64:67], v51, s[6:7] offset:16
	global_load_dwordx4 v[68:71], v51, s[6:7]
	global_load_dwordx4 v[72:75], v51, s[8:9] offset:16
	global_load_dwordx4 v[76:79], v51, s[8:9]
	global_load_dwordx4 v[130:133], v52, s[8:9]
	global_load_dwordx4 v[134:137], v52, s[8:9] offset:16
	global_load_dwordx4 v[138:141], v52, s[6:7]
	global_load_dwordx4 v[142:145], v52, s[6:7] offset:16
	global_load_dwordx4 v[146:149], v53, s[8:9]
	global_load_dwordx4 v[150:153], v53, s[8:9] offset:16
	global_load_dwordx4 v[154:157], v53, s[6:7]
	global_load_dwordx4 v[158:161], v53, s[6:7] offset:16
	global_load_dwordx4 v[162:165], v54, s[8:9]
	global_load_dwordx4 v[166:169], v54, s[8:9] offset:16
	global_load_dwordx4 v[170:173], v54, s[6:7]
	global_load_dwordx4 v[174:177], v54, s[6:7] offset:16
	v_add_co_u32_e32 v80, vcc, s10, v34
	s_add_i32 s98, s98, s101
	s_nop 0
	v_addc_co_u32_e32 v81, vcc, -1, v35, vcc
	s_cmp_lt_i32 s98, s100
	s_waitcnt vmcnt(0)
	v_cvt_f32_f16_sdwa v83, v36 dst_sel:DWORD dst_unused:UNUSED_PAD src0_sel:WORD_1
	v_cvt_f32_f16_sdwa v85, v37 dst_sel:DWORD dst_unused:UNUSED_PAD src0_sel:WORD_1
	v_cvt_f32_f16_sdwa v87, v38 dst_sel:DWORD dst_unused:UNUSED_PAD src0_sel:WORD_1
	v_cvt_f32_f16_sdwa v89, v39 dst_sel:DWORD dst_unused:UNUSED_PAD src0_sel:WORD_1
	v_cvt_f32_f16_e32 v82, v36
	v_cvt_f32_f16_e32 v84, v37
	v_cvt_f32_f16_e32 v86, v38
	v_cvt_f32_f16_e32 v88, v39
	v_cvt_f32_f16_sdwa v91, v40 dst_sel:DWORD dst_unused:UNUSED_PAD src0_sel:WORD_1
	v_cvt_f32_f16_sdwa v93, v41 dst_sel:DWORD dst_unused:UNUSED_PAD src0_sel:WORD_1
	v_cvt_f32_f16_e32 v90, v40
	v_cvt_f32_f16_e32 v92, v41
	v_cvt_f32_f16_e32 v94, v42
	v_cvt_f32_f16_e32 v96, v43
	v_cvt_f32_f16_sdwa v95, v42 dst_sel:DWORD dst_unused:UNUSED_PAD src0_sel:WORD_1
	v_cvt_f32_f16_sdwa v97, v43 dst_sel:DWORD dst_unused:UNUSED_PAD src0_sel:WORD_1
	v_cvt_f32_f16_sdwa v99, v56 dst_sel:DWORD dst_unused:UNUSED_PAD src0_sel:WORD_1
	v_cvt_f32_f16_e32 v98, v56
	v_cvt_f32_f16_sdwa v101, v57 dst_sel:DWORD dst_unused:UNUSED_PAD src0_sel:WORD_1
	v_cvt_f32_f16_e32 v100, v57
	v_cvt_f32_f16_sdwa v103, v58 dst_sel:DWORD dst_unused:UNUSED_PAD src0_sel:WORD_1
	v_cvt_f32_f16_e32 v102, v58
	v_cvt_f32_f16_sdwa v105, v59 dst_sel:DWORD dst_unused:UNUSED_PAD src0_sel:WORD_1
	v_cvt_f32_f16_e32 v104, v59
	v_cvt_f32_f16_sdwa v39, v62 dst_sel:DWORD dst_unused:UNUSED_PAD src0_sel:WORD_1
	v_cvt_f32_f16_e32 v38, v62
	v_cvt_f32_f16_sdwa v43, v63 dst_sel:DWORD dst_unused:UNUSED_PAD src0_sel:WORD_1
	v_cvt_f32_f16_e32 v42, v63
	v_mov_b32_e32 v58, v83
	v_mov_b32_e32 v59, v87
	v_mov_b32_e32 v62, v85
	v_mov_b32_e32 v63, v89
	v_cvt_f32_f16_sdwa v37, v60 dst_sel:DWORD dst_unused:UNUSED_PAD src0_sel:WORD_1
	v_cvt_f32_f16_e32 v36, v60
	v_cvt_f32_f16_sdwa v41, v61 dst_sel:DWORD dst_unused:UNUSED_PAD src0_sel:WORD_1
	v_cvt_f32_f16_e32 v40, v61
	v_mov_b32_e32 v56, v82
	v_mov_b32_e32 v57, v86
	v_mov_b32_e32 v60, v84
	v_mov_b32_e32 v61, v88
	v_mov_b32_e32 v108, v91
	v_mov_b32_e32 v109, v93
	v_pk_mul_f32 v[58:59], v[58:59], v[58:59]
	v_pk_mul_f32 v[62:63], v[62:63], v[62:63]
	v_mov_b32_e32 v106, v90
	v_mov_b32_e32 v107, v92
	v_pk_mul_f32 v[108:109], v[108:109], v[108:109]
	v_pk_fma_f32 v[56:57], v[56:57], v[56:57], v[58:59]
	v_pk_fma_f32 v[58:59], v[60:61], v[60:61], v[62:63]
	v_mul_f32_e32 v110, v94, v94
	v_mul_f32_e32 v112, v96, v96
	v_pk_fma_f32 v[60:61], v[106:107], v[106:107], v[108:109]
	v_pk_add_f32 v[56:57], v[56:57], v[58:59]
	v_pk_mul_f32 v[114:115], v[98:99], v[98:99]
	v_pk_mul_f32 v[116:117], v[100:101], v[100:101]
	v_pk_fma_f32 v[110:111], v[94:95], v[94:95], v[110:111] op_sel_hi:[1,1,0]
	v_pk_fma_f32 v[112:113], v[96:97], v[96:97], v[112:113] op_sel_hi:[1,1,0]
	v_pk_add_f32 v[58:59], v[60:61], v[60:61] op_sel_hi:[0,1]
	v_pk_add_f32 v[56:57], v[56:57], v[56:57] op_sel_hi:[0,1]
	v_mov_b32_e32 v120, v103
	v_mov_b32_e32 v121, v105
	v_mov_b32_e32 v110, v114
	v_mov_b32_e32 v112, v115
	v_mov_b32_e32 v58, v117
	v_mov_b32_e32 v56, v116
	v_mov_b32_e32 v118, v102
	v_mov_b32_e32 v119, v104
	v_pk_mul_f32 v[120:121], v[120:121], v[120:121]
	v_pk_add_f32 v[60:61], v[110:111], v[112:113]
	v_pk_add_f32 v[56:57], v[56:57], v[58:59]
	v_mul_f32_e32 v122, v36, v36
	v_mul_f32_e32 v124, v40, v40
	v_pk_fma_f32 v[62:63], v[118:119], v[118:119], v[120:121]
	v_pk_add_f32 v[56:57], v[60:61], v[56:57]
	v_pk_mul_f32 v[126:127], v[38:39], v[38:39]
	v_pk_mul_f32 v[128:129], v[42:43], v[42:43]
	v_pk_fma_f32 v[122:123], v[36:37], v[36:37], v[122:123] op_sel_hi:[1,1,0]
	v_pk_fma_f32 v[124:125], v[40:41], v[40:41], v[124:125] op_sel_hi:[1,1,0]
	v_pk_add_f32 v[62:63], v[62:63], v[62:63] op_sel_hi:[0,1]
	v_pk_add_f32 v[56:57], v[56:57], v[56:57] op_sel_hi:[0,1]
	v_mov_b32_e32 v122, v126
	v_mov_b32_e32 v124, v127
	v_mov_b32_e32 v62, v128
	v_mov_b32_e32 v56, v129
	v_pk_add_f32 v[106:107], v[122:123], v[124:125]
	v_pk_add_f32 v[56:57], v[62:63], v[56:57]
	v_pk_add_f32 v[78:79], v[78:79], 1.0 op_sel_hi:[1,0]
	v_pk_add_f32 v[56:57], v[106:107], v[56:57]
	v_pk_add_f32 v[76:77], v[76:77], 1.0 op_sel_hi:[1,0]
	v_add_f32_e32 v55, v56, v57
	ds_bpermute_b32 v56, v44, v55
	v_pk_add_f32 v[74:75], v[74:75], 1.0 op_sel_hi:[1,0]
	v_pk_add_f32 v[72:73], v[72:73], 1.0 op_sel_hi:[1,0]
	s_waitcnt lgkmcnt(0)
	v_add_f32_e32 v55, v55, v56
	ds_bpermute_b32 v56, v45, v55
	s_waitcnt lgkmcnt(0)
	v_add_f32_e32 v55, v55, v56
	ds_bpermute_b32 v56, v46, v55
	s_waitcnt lgkmcnt(0)
	v_add_f32_e32 v55, v55, v56
	ds_bpermute_b32 v56, v47, v55
	s_waitcnt lgkmcnt(0)
	v_add_f32_e32 v55, v55, v56
	ds_bpermute_b32 v56, v48, v55
	s_waitcnt lgkmcnt(0)
	v_add_f32_e32 v55, v55, v56
	ds_bpermute_b32 v56, v49, v55
	s_waitcnt lgkmcnt(0)
	v_add_f32_e32 v55, v55, v56
	v_fmamk_f32 v55, v55, 0x3a000000, v50
	v_rsq_f32_e32 v106, v55
	s_nop 0
	v_pk_mul_f32 v[56:57], v[84:85], v[106:107] op_sel_hi:[1,0]
	v_pk_mul_f32 v[58:59], v[82:83], v[106:107] op_sel_hi:[1,0]
	v_pk_mul_f32 v[60:61], v[88:89], v[106:107] op_sel_hi:[1,0]
	v_pk_mul_f32 v[62:63], v[86:87], v[106:107] op_sel_hi:[1,0]
	v_pk_mul_f32 v[58:59], v[6:7], v[58:59]
	v_pk_mul_f32 v[56:57], v[8:9], v[56:57]
	v_pk_mul_f32 v[62:63], v[2:3], v[62:63]
	v_pk_mul_f32 v[60:61], v[4:5], v[60:61]
	v_pk_fma_f32 v[70:71], v[78:79], v[56:57], v[70:71]
	v_pk_fma_f32 v[56:57], v[76:77], v[58:59], v[68:69]
	v_pk_fma_f32 v[60:61], v[74:75], v[60:61], v[66:67]
	v_pk_fma_f32 v[58:59], v[72:73], v[62:63], v[64:65]
	v_cvt_pk_bf16_f32 v56, v56, v57
	v_cvt_pk_bf16_f32 v57, v70, v71
	v_cvt_pk_bf16_f32 v58, v58, v59
	v_cvt_pk_bf16_f32 v59, v60, v61
	global_store_dwordx4 v[80:81], v[56:59], off sc1
	v_pk_mul_f32 v[74:75], v[92:93], v[106:107] op_sel_hi:[1,0]
	v_pk_mul_f32 v[76:77], v[90:91], v[106:107] op_sel_hi:[1,0]
	v_pk_mul_f32 v[78:79], v[96:97], v[106:107] op_sel_hi:[1,0]
	v_pk_mul_f32 v[80:81], v[94:95], v[106:107] op_sel_hi:[1,0]
	v_pk_mul_f32 v[76:77], v[14:15], v[76:77]
	v_pk_mul_f32 v[74:75], v[16:17], v[74:75]
	v_pk_mul_f32 v[80:81], v[10:11], v[80:81]
	v_pk_mul_f32 v[78:79], v[12:13], v[78:79]
	v_add_co_u32_e32 v72, vcc, s11, v34
	v_pk_mul_f32 v[40:41], v[40:41], v[106:107] op_sel_hi:[1,0]
	s_nop 0
	v_addc_co_u32_e32 v73, vcc, -1, v35, vcc
	v_pk_mul_f32 v[36:37], v[36:37], v[106:107] op_sel_hi:[1,0]
	v_pk_mul_f32 v[42:43], v[42:43], v[106:107] op_sel_hi:[1,0]
	v_pk_mul_f32 v[38:39], v[38:39], v[106:107] op_sel_hi:[1,0]
	v_pk_mul_f32 v[36:37], v[30:31], v[36:37]
	v_pk_mul_f32 v[40:41], v[32:33], v[40:41]
	v_pk_mul_f32 v[38:39], v[26:27], v[38:39]
	v_pk_mul_f32 v[42:43], v[28:29], v[42:43]
	v_lshl_add_u64 v[34:35], v[34:35], 0, s[0:1]
	v_pk_add_f32 v[58:59], v[132:133], 1.0 op_sel_hi:[1,0]
	v_pk_add_f32 v[56:57], v[130:131], 1.0 op_sel_hi:[1,0]
	v_pk_add_f32 v[62:63], v[136:137], 1.0 op_sel_hi:[1,0]
	v_pk_add_f32 v[60:61], v[134:135], 1.0 op_sel_hi:[1,0]
	v_pk_fma_f32 v[58:59], v[58:59], v[74:75], v[140:141]
	v_pk_fma_f32 v[56:57], v[56:57], v[76:77], v[138:139]
	v_pk_fma_f32 v[62:63], v[62:63], v[78:79], v[144:145]
	v_pk_fma_f32 v[60:61], v[60:61], v[80:81], v[142:143]
	v_cvt_pk_bf16_f32 v56, v56, v57
	v_cvt_pk_bf16_f32 v57, v58, v59
	v_cvt_pk_bf16_f32 v58, v60, v61
	v_cvt_pk_bf16_f32 v59, v62, v63
	global_store_dwordx4 v[72:73], v[56:59], off offset:-3072 sc1
	v_pk_mul_f32 v[74:75], v[100:101], v[106:107] op_sel_hi:[1,0]
	v_pk_mul_f32 v[76:77], v[98:99], v[106:107] op_sel_hi:[1,0]
	v_pk_mul_f32 v[78:79], v[104:105], v[106:107] op_sel_hi:[1,0]
	v_pk_mul_f32 v[80:81], v[102:103], v[106:107] op_sel_hi:[1,0]
	v_pk_mul_f32 v[76:77], v[22:23], v[76:77]
	v_pk_mul_f32 v[74:75], v[24:25], v[74:75]
	v_pk_mul_f32 v[80:81], v[18:19], v[80:81]
	v_pk_mul_f32 v[78:79], v[20:21], v[78:79]
	v_pk_add_f32 v[58:59], v[148:149], 1.0 op_sel_hi:[1,0]
	v_pk_add_f32 v[56:57], v[146:147], 1.0 op_sel_hi:[1,0]
	v_pk_add_f32 v[62:63], v[152:153], 1.0 op_sel_hi:[1,0]
	v_pk_add_f32 v[60:61], v[150:151], 1.0 op_sel_hi:[1,0]
	v_pk_fma_f32 v[58:59], v[58:59], v[74:75], v[156:157]
	v_pk_fma_f32 v[56:57], v[56:57], v[76:77], v[154:155]
	v_pk_fma_f32 v[62:63], v[62:63], v[78:79], v[160:161]
	v_pk_fma_f32 v[60:61], v[60:61], v[80:81], v[158:159]
	v_cvt_pk_bf16_f32 v56, v56, v57
	v_cvt_pk_bf16_f32 v57, v58, v59
	v_cvt_pk_bf16_f32 v58, v60, v61
	v_cvt_pk_bf16_f32 v59, v62, v63
	global_store_dwordx4 v[72:73], v[56:59], off offset:-2048 sc1
	v_pk_add_f32 v[62:63], v[168:169], 1.0 op_sel_hi:[1,0]
	v_pk_add_f32 v[60:61], v[166:167], 1.0 op_sel_hi:[1,0]
	s_nop 0
	v_pk_add_f32 v[58:59], v[164:165], 1.0 op_sel_hi:[1,0]
	v_pk_add_f32 v[56:57], v[162:163], 1.0 op_sel_hi:[1,0]
	v_pk_fma_f32 v[40:41], v[58:59], v[40:41], v[172:173]
	v_pk_fma_f32 v[36:37], v[56:57], v[36:37], v[170:171]
	v_pk_fma_f32 v[42:43], v[42:43], v[62:63], v[176:177]
	v_pk_fma_f32 v[38:39], v[38:39], v[60:61], v[174:175]
	v_cvt_pk_bf16_f32 v36, v36, v37
	v_cvt_pk_bf16_f32 v37, v40, v41
	v_cvt_pk_bf16_f32 v38, v38, v39
	v_cvt_pk_bf16_f32 v39, v42, v43
	global_store_dwordx4 v[72:73], v[36:39], off offset:-1024 sc1
	s_cbranch_scc1 .LBB0_921
